# attention: Q / selection-list loads and output stores marked nt (streamed once; keeps the K/V working set in L2)
# speedup vs baseline: 1.0012x; 1.0012x over previous
; __device__ __forceinline__ void phase_attn(KP kp, int l, unsigned char* shm) {
;     ...
;     const int cnt = n < 256 ? n : 256;
;     {
;       u32x2 sv = *(const u32x2*)(SEL + (size_t)r * 256 + lane * 4);
;       const int k0 = lane * 4;
;       unsigned a0 = sv[0] & 0xffffu, a1 = sv[0] >> 16, a2 = sv[1] & 0xffffu, a3 = sv[1] >> 16;
;       a0 = (k0 < cnt) ? a0 : 0u; a1 = (k0 + 1 < cnt) ? a1 : 0u; a2 = (k0 + 2 < cnt) ? a2 : 0u; a3 = (k0 + 3 < cnt) ? a3 : 0u;
;       u32x2 o;
;       o[0] = a0 | (a1 << 16); o[1] = a2 | (a3 << 16);
;       *(u32x2*)(selw + lane * 4) = o;
;     }
;     __builtin_amdgcn_wave_barrier();
;     bf16x8 kpre[8][2];
; #pragma unroll
;     for (int kvh = 0; kvh < 2; ++kvh) {
;       bf16x8 bq0, bq1;
; #pragma unroll
;       for (int e = 0; e < 8; ++e) { bq0[e] = 0; bq1[e] = 0; }
;       if (nn < 4) {
;         const bf16_t* qp = Q + (size_t)r * 512 + (kvh * 4 + nn) * 64 + kg * 8;
;         bq0 = *(const bf16x8*)qp;
;         bq1 = *(const bf16x8*)(qp + 32);
;       }
;       f32x4 lg[16];
;       for (int repQ = 0; repQ < ((PROBE & 128) ? 2 : 1); ++repQ)
;       {
; #pragma unroll
;         for (int hb = 0; hb < 2; ++hb) {
;           bf16x8 ka[8][2];
;           if (kvh == 1 && hb == 0) {
; #pragma unroll
;             for (int k8 = 0; k8 < 8; ++k8) { ka[k8][0] = kpre[k8][0]; ka[k8][1] = kpre[k8][1]; }
;           } else {
; #pragma unroll
;             for (int k8 = 0; k8 < 8; ++k8) {
;               const int idx = selw[(hb * 8 + k8) * 16 + nn];
;               const bf16_t* kp = kbase + (size_t)idx * 128 + kvh * 64 + kg * 8;
;               ka[k8][0] = *(const bf16x8*)kp;
;               ka[k8][1] = *(const bf16x8*)(kp + 32);
;             }
.Lattn_join_3:
	s_add_u32 s28, s0, s7
	s_addc_u32 s29, s1, 0
	s_add_u32 s30, s0, s8
	s_addc_u32 s31, s1, 0
	s_lshl_b32 s6, s51, 9
	s_add_u32 s6, s6, 0x1b3c2000
	s_add_u32 s38, s0, s6
	s_addc_u32 s39, s1, 0
	s_lshl_b32 s6, s51, 10
	s_add_u32 s7, s6, 0x7ac0000
	s_add_u32 s40, s0, s7
	s_addc_u32 s41, s1, 0
	s_add_u32 s7, s6, 0x1c402000
	s_add_u32 s36, s0, s7
	s_addc_u32 s37, s1, 0
	global_load_dwordx2 v[198:199], v188, s[38:39] nt
	s_mov_b64 exec, s[42:43]
	global_load_dwordx4 v[144:147], v189, s[40:41] nt
	global_load_dwordx4 v[148:151], v189, s[40:41] offset:64 nt
	global_load_dwordx4 v[152:155], v189, s[40:41] offset:512 nt
	global_load_dwordx4 v[156:159], v189, s[40:41] offset:576 nt
	s_mov_b64 exec, -1
	s_waitcnt vmcnt(0)
	s_lshr_b32 s6, s45, 2
	v_cmp_gt_u32_e32 vcc, s6, v252
	s_nop 1
	v_cndmask_b32_e32 v198, 0, v198, vcc
	v_cndmask_b32_e32 v199, 0, v199, vcc
	ds_write_b64 v186, v[198:199]
	ds_read_u16 v0, v187 offset:0
	ds_read_u16 v1, v187 offset:16
	ds_read_u16 v2, v187 offset:32
	ds_read_u16 v3, v187 offset:48
	ds_read_u16 v4, v187 offset:64
	ds_read_u16 v5, v187 offset:80
	ds_read_u16 v6, v187 offset:96
	ds_read_u16 v7, v187 offset:112
	s_waitcnt lgkmcnt(0)
	v_lshl_add_u32 v0, v0, 8, v193
	v_lshl_add_u32 v1, v1, 8, v194
	v_lshl_add_u32 v2, v2, 8, v195
	v_lshl_add_u32 v3, v3, 8, v196
	v_lshl_add_u32 v4, v4, 8, v193
	v_lshl_add_u32 v5, v5, 8, v194
	v_lshl_add_u32 v6, v6, 8, v195
	v_lshl_add_u32 v7, v7, 8, v196
	ds_read_u16 v8, v187 offset:128
	ds_read_u16 v9, v187 offset:144
	ds_read_u16 v10, v187 offset:160
	ds_read_u16 v11, v187 offset:176
	ds_read_u16 v12, v187 offset:192
	ds_read_u16 v13, v187 offset:208
	ds_read_u16 v14, v187 offset:224
	ds_read_u16 v15, v187 offset:240
	s_waitcnt lgkmcnt(0)
	v_lshl_add_u32 v8, v8, 8, v193
	v_lshl_add_u32 v9, v9, 8, v194
	v_lshl_add_u32 v10, v10, 8, v195
	v_lshl_add_u32 v11, v11, 8, v196
	v_lshl_add_u32 v12, v12, 8, v193
	v_lshl_add_u32 v13, v13, 8, v194
	v_lshl_add_u32 v14, v14, 8, v195
	v_lshl_add_u32 v15, v15, 8, v196
	ds_read_u16 v16, v187 offset:256
	ds_read_u16 v18, v187 offset:272
	ds_read_u16 v19, v187 offset:288
	ds_read_u16 v20, v187 offset:304
	ds_read_u16 v21, v187 offset:320
	ds_read_u16 v22, v187 offset:336
	ds_read_u16 v23, v187 offset:352
	ds_read_u16 v24, v187 offset:368
	s_waitcnt lgkmcnt(0)
	v_lshl_add_u32 v16, v16, 8, v193
	v_lshl_add_u32 v18, v18, 8, v194
	v_lshl_add_u32 v19, v19, 8, v195
	v_lshl_add_u32 v20, v20, 8, v196
	v_lshl_add_u32 v21, v21, 8, v193
	v_lshl_add_u32 v22, v22, 8, v194
	v_lshl_add_u32 v23, v23, 8, v195
	v_lshl_add_u32 v24, v24, 8, v196
	ds_read_u16 v25, v187 offset:384
	ds_read_u16 v26, v187 offset:400
	ds_read_u16 v27, v187 offset:416
	ds_read_u16 v28, v187 offset:432
	ds_read_u16 v29, v187 offset:448
	ds_read_u16 v30, v187 offset:464
	ds_read_u16 v31, v187 offset:480
	ds_read_u16 v219, v187 offset:496
	s_waitcnt lgkmcnt(0)
	v_lshl_add_u32 v25, v25, 8, v193
	v_lshl_add_u32 v26, v26, 8, v194
	v_lshl_add_u32 v27, v27, 8, v195
	v_lshl_add_u32 v28, v28, 8, v196
	v_lshl_add_u32 v29, v29, 8, v193
	v_lshl_add_u32 v30, v30, 8, v194
	v_lshl_add_u32 v31, v31, 8, v195
	v_lshl_add_u32 v219, v219, 8, v196
	s_mov_b32 m0, s46
	s_nop 0
	global_load_lds_dwordx4 v0, s[28:29]
	global_load_lds_dwordx4 v1, s[28:29] offset:1024
	global_load_lds_dwordx4 v2, s[28:29] offset:2048
	global_load_lds_dwordx4 v3, s[28:29] offset:3072
	s_mov_b32 m0, s47
	s_nop 0
	global_load_lds_dwordx4 v4, s[28:29]
	global_load_lds_dwordx4 v5, s[28:29] offset:1024
	global_load_lds_dwordx4 v6, s[28:29] offset:2048
	global_load_lds_dwordx4 v7, s[28:29] offset:3072
	s_mov_b32 m0, s48
	s_nop 0
	global_load_lds_dwordx4 v8, s[28:29]
	global_load_lds_dwordx4 v9, s[28:29] offset:1024
	global_load_lds_dwordx4 v10, s[28:29] offset:2048
	global_load_lds_dwordx4 v11, s[28:29] offset:3072
	global_load_dword v209, v17, s[0:1]
	global_load_dword v209, v17, s[0:1]
	global_load_dword v209, v17, s[0:1]
	global_load_dword v209, v17, s[0:1]
	s_mov_b64 s[20:21], s[28:29]
	s_mov_b64 s[22:23], s[30:31]
	s_add_u32 s24, s28, 0x80
	s_addc_u32 s25, s29, 0
	s_add_u32 s26, s30, 0x80
	s_addc_u32 s27, s31, 0
	s_mov_b64 s[34:35], s[36:37]
	s_mov_b32 s44, s45

; __device__ __forceinline__ void phase_attn(KP kp, int l, unsigned char* shm) {
;     ...
;       float mx = -1e30f;
; #pragma unroll
;       for (int kb = 0; kb < 16; ++kb)
; #pragma unroll
;         for (int j = 0; j < 4; ++j) {
;           const int key = kb * 16 + kg * 4 + j;
;           lg[kb][j] = key < cnt ? lg[kb][j] : -1e30f;
;           mx = fmaxf(mx, lg[kb][j]);
;         }
;       mx = fmaxf(mx, __shfl_xor(mx, 16));
;       mx = fmaxf(mx, __shfl_xor(mx, 32));
;       float sum = 0.f;
; #pragma unroll
;       for (int kb = 0; kb < 16; ++kb)
; #pragma unroll
;         for (int j = 0; j < 4; ++j) { lg[kb][j] = __builtin_amdgcn_exp2f(lg[kb][j] - mx); sum += lg[kb][j]; }
.Lattn_nomask_4:
	v_max3_f32 v176, v32, v33, v34
	v_max3_f32 v176, v176, v35, v36
	v_max3_f32 v176, v176, v37, v38
	v_max3_f32 v176, v176, v39, v40
	v_max3_f32 v176, v176, v41, v42
	v_max3_f32 v176, v176, v43, v44
	v_max3_f32 v176, v176, v45, v46
	v_max3_f32 v176, v176, v47, v48
	v_max3_f32 v176, v176, v49, v50
	v_max3_f32 v176, v176, v51, v52
	v_max3_f32 v176, v176, v53, v54
	v_max3_f32 v176, v176, v55, v56
	v_max3_f32 v176, v176, v57, v58
	v_max3_f32 v176, v176, v59, v60
	v_max3_f32 v176, v176, v61, v62
	v_max3_f32 v176, v176, v63, v64
	v_max3_f32 v176, v176, v65, v66
	v_max3_f32 v176, v176, v67, v68
	v_max3_f32 v176, v176, v69, v70
	v_max3_f32 v176, v176, v71, v72
	v_max3_f32 v176, v176, v73, v74
	v_max3_f32 v176, v176, v75, v76
	v_max3_f32 v176, v176, v77, v78
	v_max3_f32 v176, v176, v79, v80
	v_max3_f32 v176, v176, v81, v82
	v_max3_f32 v176, v176, v83, v84
	v_max3_f32 v176, v176, v85, v86
	v_max3_f32 v176, v176, v87, v88
	v_max3_f32 v176, v176, v89, v90
	v_max3_f32 v176, v176, v91, v92
	v_max3_f32 v176, v176, v93, v94
	v_max_f32_e32 v176, v176, v95
	ds_bpermute_b32 v197, v191, v176
	s_waitcnt lgkmcnt(0)
	v_max_f32_e32 v176, v176, v197
	ds_bpermute_b32 v197, v192, v176
	s_waitcnt lgkmcnt(0)
	v_max_f32_e32 v176, v176, v197
	v_mov_b32_e32 v177, v176
	v_pk_add_f32 v[32:33], v[32:33], v[176:177] neg_lo:[0,1] neg_hi:[0,1]
	v_pk_add_f32 v[34:35], v[34:35], v[176:177] neg_lo:[0,1] neg_hi:[0,1]
	v_pk_add_f32 v[36:37], v[36:37], v[176:177] neg_lo:[0,1] neg_hi:[0,1]
	v_pk_add_f32 v[38:39], v[38:39], v[176:177] neg_lo:[0,1] neg_hi:[0,1]
	v_pk_add_f32 v[40:41], v[40:41], v[176:177] neg_lo:[0,1] neg_hi:[0,1]
	v_pk_add_f32 v[42:43], v[42:43], v[176:177] neg_lo:[0,1] neg_hi:[0,1]
	v_pk_add_f32 v[44:45], v[44:45], v[176:177] neg_lo:[0,1] neg_hi:[0,1]
	v_pk_add_f32 v[46:47], v[46:47], v[176:177] neg_lo:[0,1] neg_hi:[0,1]
	v_pk_add_f32 v[48:49], v[48:49], v[176:177] neg_lo:[0,1] neg_hi:[0,1]
	v_pk_add_f32 v[50:51], v[50:51], v[176:177] neg_lo:[0,1] neg_hi:[0,1]
	v_pk_add_f32 v[52:53], v[52:53], v[176:177] neg_lo:[0,1] neg_hi:[0,1]
	v_pk_add_f32 v[54:55], v[54:55], v[176:177] neg_lo:[0,1] neg_hi:[0,1]
	v_pk_add_f32 v[56:57], v[56:57], v[176:177] neg_lo:[0,1] neg_hi:[0,1]
	v_pk_add_f32 v[58:59], v[58:59], v[176:177] neg_lo:[0,1] neg_hi:[0,1]
	v_pk_add_f32 v[60:61], v[60:61], v[176:177] neg_lo:[0,1] neg_hi:[0,1]
	v_pk_add_f32 v[62:63], v[62:63], v[176:177] neg_lo:[0,1] neg_hi:[0,1]
	v_pk_add_f32 v[64:65], v[64:65], v[176:177] neg_lo:[0,1] neg_hi:[0,1]
	v_pk_add_f32 v[66:67], v[66:67], v[176:177] neg_lo:[0,1] neg_hi:[0,1]
	v_pk_add_f32 v[68:69], v[68:69], v[176:177] neg_lo:[0,1] neg_hi:[0,1]
	v_pk_add_f32 v[70:71], v[70:71], v[176:177] neg_lo:[0,1] neg_hi:[0,1]
	v_pk_add_f32 v[72:73], v[72:73], v[176:177] neg_lo:[0,1] neg_hi:[0,1]
	v_pk_add_f32 v[74:75], v[74:75], v[176:177] neg_lo:[0,1] neg_hi:[0,1]
	v_pk_add_f32 v[76:77], v[76:77], v[176:177] neg_lo:[0,1] neg_hi:[0,1]
	v_pk_add_f32 v[78:79], v[78:79], v[176:177] neg_lo:[0,1] neg_hi:[0,1]
	v_pk_add_f32 v[80:81], v[80:81], v[176:177] neg_lo:[0,1] neg_hi:[0,1]
	v_pk_add_f32 v[82:83], v[82:83], v[176:177] neg_lo:[0,1] neg_hi:[0,1]
	v_pk_add_f32 v[84:85], v[84:85], v[176:177] neg_lo:[0,1] neg_hi:[0,1]
	v_pk_add_f32 v[86:87], v[86:87], v[176:177] neg_lo:[0,1] neg_hi:[0,1]
	v_pk_add_f32 v[88:89], v[88:89], v[176:177] neg_lo:[0,1] neg_hi:[0,1]
	v_pk_add_f32 v[90:91], v[90:91], v[176:177] neg_lo:[0,1] neg_hi:[0,1]
	v_pk_add_f32 v[92:93], v[92:93], v[176:177] neg_lo:[0,1] neg_hi:[0,1]
	v_pk_add_f32 v[94:95], v[94:95], v[176:177] neg_lo:[0,1] neg_hi:[0,1]
	v_exp_f32_e32 v32, v32
	v_exp_f32_e32 v33, v33
	v_exp_f32_e32 v34, v34
	v_exp_f32_e32 v35, v35
	v_exp_f32_e32 v36, v36
	v_exp_f32_e32 v37, v37
	v_pk_add_f32 v[178:179], v[32:33], v[34:35]
	v_exp_f32_e32 v38, v38
	v_exp_f32_e32 v39, v39
	v_pk_add_f32 v[178:179], v[178:179], v[36:37]
	v_exp_f32_e32 v40, v40
	v_exp_f32_e32 v41, v41
	v_pk_add_f32 v[178:179], v[178:179], v[38:39]
	v_exp_f32_e32 v42, v42
	v_exp_f32_e32 v43, v43
	v_pk_add_f32 v[178:179], v[178:179], v[40:41]
	v_exp_f32_e32 v44, v44
	v_exp_f32_e32 v45, v45
	v_pk_add_f32 v[178:179], v[178:179], v[42:43]
	v_exp_f32_e32 v46, v46
	v_exp_f32_e32 v47, v47
	v_pk_add_f32 v[178:179], v[178:179], v[44:45]
	v_exp_f32_e32 v48, v48
	v_exp_f32_e32 v49, v49
	v_pk_add_f32 v[178:179], v[178:179], v[46:47]
	v_exp_f32_e32 v50, v50
	v_exp_f32_e32 v51, v51
	v_pk_add_f32 v[178:179], v[178:179], v[48:49]
	v_exp_f32_e32 v52, v52
	v_exp_f32_e32 v53, v53
	v_pk_add_f32 v[178:179], v[178:179], v[50:51]
	v_exp_f32_e32 v54, v54
	v_exp_f32_e32 v55, v55
	v_pk_add_f32 v[178:179], v[178:179], v[52:53]
	v_exp_f32_e32 v56, v56
	v_exp_f32_e32 v57, v57
	v_pk_add_f32 v[178:179], v[178:179], v[54:55]
	v_exp_f32_e32 v58, v58
	v_exp_f32_e32 v59, v59
	v_pk_add_f32 v[178:179], v[178:179], v[56:57]
	v_exp_f32_e32 v60, v60
	v_exp_f32_e32 v61, v61
	v_pk_add_f32 v[178:179], v[178:179], v[58:59]
	v_exp_f32_e32 v62, v62
	v_exp_f32_e32 v63, v63
	v_pk_add_f32 v[178:179], v[178:179], v[60:61]
	v_exp_f32_e32 v64, v64
	v_exp_f32_e32 v65, v65
	v_pk_add_f32 v[178:179], v[178:179], v[62:63]
	v_exp_f32_e32 v66, v66
	v_exp_f32_e32 v67, v67
	v_pk_add_f32 v[178:179], v[178:179], v[64:65]
	v_exp_f32_e32 v68, v68
	v_exp_f32_e32 v69, v69
	v_pk_add_f32 v[178:179], v[178:179], v[66:67]
	v_exp_f32_e32 v70, v70
	v_exp_f32_e32 v71, v71
	v_pk_add_f32 v[178:179], v[178:179], v[68:69]
	v_exp_f32_e32 v72, v72
	v_exp_f32_e32 v73, v73
	v_pk_add_f32 v[178:179], v[178:179], v[70:71]
	v_exp_f32_e32 v74, v74
	v_exp_f32_e32 v75, v75
	v_pk_add_f32 v[178:179], v[178:179], v[72:73]
	v_exp_f32_e32 v76, v76
	v_exp_f32_e32 v77, v77
	v_pk_add_f32 v[178:179], v[178:179], v[74:75]
; __device__ __forceinline__ void phase_attn(KP kp, int l, unsigned char* shm) {
;     ...
;       float sum = 0.f;
; #pragma unroll
;       for (int kb = 0; kb < 16; ++kb)
; #pragma unroll
;         for (int j = 0; j < 4; ++j) { lg[kb][j] = __builtin_amdgcn_exp2f(lg[kb][j] - mx); sum += lg[kb][j]; }
;       sum += __shfl_xor(sum, 16);
;       sum += __shfl_xor(sum, 32);
;       const float inv = 1.f / sum;
;       bf16x8 pf[8];
; #pragma unroll
;       for (int s8 = 0; s8 < 8; ++s8) {
;         u32x4 pk;
;         pk[0] = cvt_pk_bf16(lg[2 * s8][0], lg[2 * s8][1]);
;         pk[1] = cvt_pk_bf16(lg[2 * s8][2], lg[2 * s8][3]);
;         pk[2] = cvt_pk_bf16(lg[2 * s8 + 1][0], lg[2 * s8 + 1][1]);
;         pk[3] = cvt_pk_bf16(lg[2 * s8 + 1][2], lg[2 * s8 + 1][3]);
;         pf[s8] = __builtin_bit_cast(bf16x8, pk);
;       }
;       f32x4 oacc[4];
; #pragma unroll
;       for (int c = 0; c < 4; ++c) oacc[c] = (f32x4){0.f, 0.f, 0.f, 0.f};
;       for (int repV = 0; repV < ((PROBE & 256) ? 2 : 1); ++repV)
;       {
;         if (repV) {
; #pragma unroll
;           for (int c = 0; c < 4; ++c) oacc[c] = (f32x4){0.f, 0.f, 0.f, 0.f};
;         }
; #pragma unroll
;         for (int i = 16; i < 32; ++i) {
;           const int idx = selw[i * 8 + ks8];
;           vr[i] = *(const u32x4*)(vbase + (size_t)idx * 128 + kvh * 64 + dc * 8);
;         }
; #pragma unroll
;         for (int s8 = 0; s8 < 8; ++s8) {
; #pragma unroll
;           for (int it = 0; it < 4; ++it) *(u32x4*)(tileb + (it * 8 + ks8) * 144 + dc * 16) = vr[s8 * 4 + it];
;           u32x2 t0, t1, t2, t3, t4, t5, t6, t7;
;           asm volatile(
;               "ds_read_b64_tr_b16 %0, %8\n\tds_read_b64_tr_b16 %1, %8 offset:2304\n\t"
;               "ds_read_b64_tr_b16 %2, %8 offset:32\n\tds_read_b64_tr_b16 %3, %8 offset:2336\n\t"
;               "ds_read_b64_tr_b16 %4, %8 offset:64\n\tds_read_b64_tr_b16 %5, %8 offset:2368\n\t"
;               "ds_read_b64_tr_b16 %6, %8 offset:96\n\tds_read_b64_tr_b16 %7, %8 offset:2400\n\t"
;               "s_waitcnt lgkmcnt(0)"
;               : "=&v"(t0), "=&v"(t1), "=&v"(t2), "=&v"(t3), "=&v"(t4), "=&v"(t5), "=&v"(t6), "=&v"(t7)
;               : "v"(tr_addr)
;               : "memory");
;           const bf16x8 a0 = __builtin_bit_cast(bf16x8, (u32x4){t0[0], t0[1], t1[0], t1[1]});
;           const bf16x8 a1 = __builtin_bit_cast(bf16x8, (u32x4){t2[0], t2[1], t3[0], t3[1]});
	v_exp_f32_e32 v78, v78
	v_exp_f32_e32 v79, v79
	v_pk_add_f32 v[178:179], v[178:179], v[76:77]
	v_exp_f32_e32 v80, v80
	v_exp_f32_e32 v81, v81
	v_pk_add_f32 v[178:179], v[178:179], v[78:79]
	v_exp_f32_e32 v82, v82
	v_exp_f32_e32 v83, v83
	v_pk_add_f32 v[178:179], v[178:179], v[80:81]
	v_exp_f32_e32 v84, v84
	v_exp_f32_e32 v85, v85
	v_pk_add_f32 v[178:179], v[178:179], v[82:83]
	v_exp_f32_e32 v86, v86
	v_exp_f32_e32 v87, v87
	v_pk_add_f32 v[178:179], v[178:179], v[84:85]
	v_exp_f32_e32 v88, v88
	v_exp_f32_e32 v89, v89
	v_pk_add_f32 v[178:179], v[178:179], v[86:87]
	v_exp_f32_e32 v90, v90
	v_exp_f32_e32 v91, v91
	v_pk_add_f32 v[178:179], v[178:179], v[88:89]
	v_exp_f32_e32 v92, v92
	v_exp_f32_e32 v93, v93
	v_pk_add_f32 v[178:179], v[178:179], v[90:91]
	v_exp_f32_e32 v94, v94
	v_exp_f32_e32 v95, v95
	v_pk_add_f32 v[178:179], v[178:179], v[92:93]
	s_nop 0
	v_pk_add_f32 v[178:179], v[178:179], v[94:95]
	v_add_f32_e32 v210, v178, v179
	ds_bpermute_b32 v197, v191, v210
	v_cvt_pk_bf16_f32 v96, v32, v33
	v_cvt_pk_bf16_f32 v97, v34, v35
	v_cvt_pk_bf16_f32 v98, v36, v37
	v_cvt_pk_bf16_f32 v99, v38, v39
	v_cvt_pk_bf16_f32 v100, v40, v41
	v_cvt_pk_bf16_f32 v101, v42, v43
	v_cvt_pk_bf16_f32 v102, v44, v45
	v_cvt_pk_bf16_f32 v103, v46, v47
	v_cvt_pk_bf16_f32 v104, v48, v49
	v_cvt_pk_bf16_f32 v105, v50, v51
	v_cvt_pk_bf16_f32 v106, v52, v53
	v_cvt_pk_bf16_f32 v107, v54, v55
	v_cvt_pk_bf16_f32 v108, v56, v57
	v_cvt_pk_bf16_f32 v109, v58, v59
	v_cvt_pk_bf16_f32 v110, v60, v61
	v_cvt_pk_bf16_f32 v111, v62, v63
	s_waitcnt lgkmcnt(0)
	v_add_f32_e32 v210, v210, v197
	ds_bpermute_b32 v197, v192, v210
	v_cvt_pk_bf16_f32 v112, v64, v65
	v_cvt_pk_bf16_f32 v113, v66, v67
	v_cvt_pk_bf16_f32 v114, v68, v69
	v_cvt_pk_bf16_f32 v115, v70, v71
	v_cvt_pk_bf16_f32 v116, v72, v73
	v_cvt_pk_bf16_f32 v117, v74, v75
	v_cvt_pk_bf16_f32 v118, v76, v77
	v_cvt_pk_bf16_f32 v119, v78, v79
	v_cvt_pk_bf16_f32 v120, v80, v81
	v_cvt_pk_bf16_f32 v121, v82, v83
	v_cvt_pk_bf16_f32 v122, v84, v85
	v_cvt_pk_bf16_f32 v123, v86, v87
	v_cvt_pk_bf16_f32 v124, v88, v89
	v_cvt_pk_bf16_f32 v125, v90, v91
	v_cvt_pk_bf16_f32 v126, v92, v93
	v_cvt_pk_bf16_f32 v127, v94, v95
	s_waitcnt lgkmcnt(0)
	v_add_f32_e32 v210, v210, v197
	v_rcp_f32_e32 v208, v210
	s_waitcnt vmcnt(8)
	ds_read_b64_tr_b16 v[160:161], v182 offset:0
	ds_read_b64_tr_b16 v[162:163], v182 offset:2048
	ds_read_b64_tr_b16 v[164:165], v183 offset:0
	ds_read_b64_tr_b16 v[166:167], v183 offset:2048
	ds_read_b64_tr_b16 v[168:169], v184 offset:0
	ds_read_b64_tr_b16 v[170:171], v184 offset:2048
	ds_read_b64_tr_b16 v[172:173], v185 offset:0
	ds_read_b64_tr_b16 v[174:175], v185 offset:2048
	s_mov_b32 m0, s49
	s_nop 0
	global_load_lds_dwordx4 v12, s[22:23]
	global_load_lds_dwordx4 v13, s[22:23] offset:1024
	global_load_lds_dwordx4 v14, s[22:23] offset:2048
	global_load_lds_dwordx4 v15, s[22:23] offset:3072
	s_waitcnt lgkmcnt(0)
	v_mfma_f32_16x16x32_bf16 v[128:131], v[160:163], v[96:99], 0
	v_mfma_f32_16x16x32_bf16 v[132:135], v[164:167], v[96:99], 0
	v_mfma_f32_16x16x32_bf16 v[136:139], v[168:171], v[96:99], 0
	v_mfma_f32_16x16x32_bf16 v[140:143], v[172:175], v[96:99], 0
	s_waitcnt vmcnt(8)
	ds_read_b64_tr_b16 v[160:161], v182 offset:4096
	ds_read_b64_tr_b16 v[162:163], v182 offset:6144
	ds_read_b64_tr_b16 v[164:165], v183 offset:4096
	ds_read_b64_tr_b16 v[166:167], v183 offset:6144
	ds_read_b64_tr_b16 v[168:169], v184 offset:4096
	ds_read_b64_tr_b16 v[170:171], v184 offset:6144
	ds_read_b64_tr_b16 v[172:173], v185 offset:4096
	ds_read_b64_tr_b16 v[174:175], v185 offset:6144
	s_mov_b32 m0, s46
	s_nop 0
	global_load_lds_dwordx4 v16, s[22:23]
	global_load_lds_dwordx4 v18, s[22:23] offset:1024
	global_load_lds_dwordx4 v19, s[22:23] offset:2048
	global_load_lds_dwordx4 v20, s[22:23] offset:3072
	s_waitcnt lgkmcnt(0)
	v_mfma_f32_16x16x32_bf16 v[128:131], v[160:163], v[100:103], v[128:131]
	v_mfma_f32_16x16x32_bf16 v[132:135], v[164:167], v[100:103], v[132:135]
	v_mfma_f32_16x16x32_bf16 v[136:139], v[168:171], v[100:103], v[136:139]
	v_mfma_f32_16x16x32_bf16 v[140:143], v[172:175], v[100:103], v[140:143]
	s_waitcnt vmcnt(8)
	ds_read_b64_tr_b16 v[160:161], v182 offset:8192
	ds_read_b64_tr_b16 v[162:163], v182 offset:10240
	ds_read_b64_tr_b16 v[164:165], v183 offset:8192
	ds_read_b64_tr_b16 v[166:167], v183 offset:10240
	ds_read_b64_tr_b16 v[168:169], v184 offset:8192
	ds_read_b64_tr_b16 v[170:171], v184 offset:10240
	ds_read_b64_tr_b16 v[172:173], v185 offset:8192
	ds_read_b64_tr_b16 v[174:175], v185 offset:10240
	s_mov_b32 m0, s47
	s_nop 0
	global_load_lds_dwordx4 v21, s[22:23]
	global_load_lds_dwordx4 v22, s[22:23] offset:1024
	global_load_lds_dwordx4 v23, s[22:23] offset:2048
	global_load_lds_dwordx4 v24, s[22:23] offset:3072
	s_waitcnt lgkmcnt(0)
	v_mfma_f32_16x16x32_bf16 v[128:131], v[160:163], v[104:107], v[128:131]
	v_mfma_f32_16x16x32_bf16 v[132:135], v[164:167], v[104:107], v[132:135]
	v_mfma_f32_16x16x32_bf16 v[136:139], v[168:171], v[104:107], v[136:139]
	v_mfma_f32_16x16x32_bf16 v[140:143], v[172:175], v[104:107], v[140:143]
	s_waitcnt vmcnt(8)
	ds_read_b64_tr_b16 v[160:161], v182 offset:12288
	ds_read_b64_tr_b16 v[162:163], v182 offset:14336
	ds_read_b64_tr_b16 v[164:165], v183 offset:12288
	ds_read_b64_tr_b16 v[166:167], v183 offset:14336
	ds_read_b64_tr_b16 v[168:169], v184 offset:12288
	ds_read_b64_tr_b16 v[170:171], v184 offset:14336
	ds_read_b64_tr_b16 v[172:173], v185 offset:12288
	ds_read_b64_tr_b16 v[174:175], v185 offset:14336
	s_mov_b32 m0, s48
	s_nop 0
	global_load_lds_dwordx4 v25, s[22:23]
	global_load_lds_dwordx4 v26, s[22:23] offset:1024
	global_load_lds_dwordx4 v27, s[22:23] offset:2048
	global_load_lds_dwordx4 v28, s[22:23] offset:3072
	s_waitcnt lgkmcnt(0)
; __device__ __forceinline__ void phase_attn(KP kp, int l, unsigned char* shm) {
;     ...
;         for (int i = 16; i < 32; ++i) {
;           const int idx = selw[i * 8 + ks8];
;           vr[i] = *(const u32x4*)(vbase + (size_t)idx * 128 + kvh * 64 + dc * 8);
;         }
; #pragma unroll
;         for (int s8 = 0; s8 < 8; ++s8) {
; #pragma unroll
;           for (int it = 0; it < 4; ++it) *(u32x4*)(tileb + (it * 8 + ks8) * 144 + dc * 16) = vr[s8 * 4 + it];
;           u32x2 t0, t1, t2, t3, t4, t5, t6, t7;
;           asm volatile(
;               "ds_read_b64_tr_b16 %0, %8\n\tds_read_b64_tr_b16 %1, %8 offset:2304\n\t"
;               "ds_read_b64_tr_b16 %2, %8 offset:32\n\tds_read_b64_tr_b16 %3, %8 offset:2336\n\t"
;               "ds_read_b64_tr_b16 %4, %8 offset:64\n\tds_read_b64_tr_b16 %5, %8 offset:2368\n\t"
;               "ds_read_b64_tr_b16 %6, %8 offset:96\n\tds_read_b64_tr_b16 %7, %8 offset:2400\n\t"
;               "s_waitcnt lgkmcnt(0)"
;               : "=&v"(t0), "=&v"(t1), "=&v"(t2), "=&v"(t3), "=&v"(t4), "=&v"(t5), "=&v"(t6), "=&v"(t7)
;               : "v"(tr_addr)
;               : "memory");
;           const bf16x8 a0 = __builtin_bit_cast(bf16x8, (u32x4){t0[0], t0[1], t1[0], t1[1]});
;           const bf16x8 a1 = __builtin_bit_cast(bf16x8, (u32x4){t2[0], t2[1], t3[0], t3[1]});
;           const bf16x8 a2 = __builtin_bit_cast(bf16x8, (u32x4){t4[0], t4[1], t5[0], t5[1]});
;           const bf16x8 a3 = __builtin_bit_cast(bf16x8, (u32x4){t6[0], t6[1], t7[0], t7[1]});
;           oacc[0] = __builtin_amdgcn_mfma_f32_16x16x32_bf16(a0, pf[s8], oacc[0], 0, 0, 0);
;           oacc[1] = __builtin_amdgcn_mfma_f32_16x16x32_bf16(a1, pf[s8], oacc[1], 0, 0, 0);
;           oacc[2] = __builtin_amdgcn_mfma_f32_16x16x32_bf16(a2, pf[s8], oacc[2], 0, 0, 0);
;           oacc[3] = __builtin_amdgcn_mfma_f32_16x16x32_bf16(a3, pf[s8], oacc[3], 0, 0, 0);
;           if (kvh == 0 && s8 == 3) {
; #pragma unroll
;             for (int k8 = 0; k8 < 8; ++k8) {
;               const int idx = selw[k8 * 16 + nn];
;               const bf16_t* kp = kbase + (size_t)idx * 128 + 64 + kg * 8;
;               kpre[k8][0] = *(const bf16x8*)kp;
;               kpre[k8][1] = *(const bf16x8*)(kp + 32);
;             }
;           }
;         }
;         __builtin_amdgcn_sched_barrier(0);
;       }
;       if (nn < 4) {
; #pragma unroll
;         for (int c = 0; c < 4; ++c) {
	v_mfma_f32_16x16x32_bf16 v[128:131], v[160:163], v[108:111], v[128:131]
	v_mfma_f32_16x16x32_bf16 v[132:135], v[164:167], v[108:111], v[132:135]
	v_mfma_f32_16x16x32_bf16 v[136:139], v[168:171], v[108:111], v[136:139]
	v_mfma_f32_16x16x32_bf16 v[140:143], v[172:175], v[108:111], v[140:143]
	s_waitcnt vmcnt(8)
	ds_read_b64_tr_b16 v[160:161], v182 offset:0
	ds_read_b64_tr_b16 v[162:163], v182 offset:2048
	ds_read_b64_tr_b16 v[164:165], v183 offset:0
	ds_read_b64_tr_b16 v[166:167], v183 offset:2048
	ds_read_b64_tr_b16 v[168:169], v184 offset:0
	ds_read_b64_tr_b16 v[170:171], v184 offset:2048
	ds_read_b64_tr_b16 v[172:173], v185 offset:0
	ds_read_b64_tr_b16 v[174:175], v185 offset:2048
	s_mov_b32 m0, s49
	s_nop 0
	global_load_lds_dwordx4 v29, s[22:23]
	global_load_lds_dwordx4 v30, s[22:23] offset:1024
	global_load_lds_dwordx4 v31, s[22:23] offset:2048
	global_load_lds_dwordx4 v219, s[22:23] offset:3072
	s_waitcnt lgkmcnt(0)
	v_mfma_f32_16x16x32_bf16 v[128:131], v[160:163], v[112:115], v[128:131]
	v_mfma_f32_16x16x32_bf16 v[132:135], v[164:167], v[112:115], v[132:135]
	v_mfma_f32_16x16x32_bf16 v[136:139], v[168:171], v[112:115], v[136:139]
	v_mfma_f32_16x16x32_bf16 v[140:143], v[172:175], v[112:115], v[140:143]
	s_waitcnt vmcnt(8)
	ds_read_b64_tr_b16 v[160:161], v182 offset:4096
	ds_read_b64_tr_b16 v[162:163], v182 offset:6144
	ds_read_b64_tr_b16 v[164:165], v183 offset:4096
	ds_read_b64_tr_b16 v[166:167], v183 offset:6144
	ds_read_b64_tr_b16 v[168:169], v184 offset:4096
	ds_read_b64_tr_b16 v[170:171], v184 offset:6144
	ds_read_b64_tr_b16 v[172:173], v185 offset:4096
	ds_read_b64_tr_b16 v[174:175], v185 offset:6144
	s_mov_b32 m0, s46
	s_nop 0
	global_load_lds_dwordx4 v0, s[24:25]
	global_load_lds_dwordx4 v1, s[24:25] offset:1024
	global_load_lds_dwordx4 v2, s[24:25] offset:2048
	global_load_lds_dwordx4 v3, s[24:25] offset:3072
	s_waitcnt lgkmcnt(0)
	v_mfma_f32_16x16x32_bf16 v[128:131], v[160:163], v[116:119], v[128:131]
	v_mfma_f32_16x16x32_bf16 v[132:135], v[164:167], v[116:119], v[132:135]
	v_mfma_f32_16x16x32_bf16 v[136:139], v[168:171], v[116:119], v[136:139]
	v_mfma_f32_16x16x32_bf16 v[140:143], v[172:175], v[116:119], v[140:143]
	s_waitcnt vmcnt(8)
	ds_read_b64_tr_b16 v[160:161], v182 offset:8192
	ds_read_b64_tr_b16 v[162:163], v182 offset:10240
	ds_read_b64_tr_b16 v[164:165], v183 offset:8192
	ds_read_b64_tr_b16 v[166:167], v183 offset:10240
	ds_read_b64_tr_b16 v[168:169], v184 offset:8192
	ds_read_b64_tr_b16 v[170:171], v184 offset:10240
	ds_read_b64_tr_b16 v[172:173], v185 offset:8192
	ds_read_b64_tr_b16 v[174:175], v185 offset:10240
	s_mov_b32 m0, s47
	s_nop 0
	global_load_lds_dwordx4 v4, s[24:25]
	global_load_lds_dwordx4 v5, s[24:25] offset:1024
	global_load_lds_dwordx4 v6, s[24:25] offset:2048
	global_load_lds_dwordx4 v7, s[24:25] offset:3072
	s_waitcnt lgkmcnt(0)
	v_mfma_f32_16x16x32_bf16 v[128:131], v[160:163], v[120:123], v[128:131]
	v_mfma_f32_16x16x32_bf16 v[132:135], v[164:167], v[120:123], v[132:135]
	v_mfma_f32_16x16x32_bf16 v[136:139], v[168:171], v[120:123], v[136:139]
	v_mfma_f32_16x16x32_bf16 v[140:143], v[172:175], v[120:123], v[140:143]
	s_waitcnt vmcnt(8)
	ds_read_b64_tr_b16 v[160:161], v182 offset:12288
	ds_read_b64_tr_b16 v[162:163], v182 offset:14336
	ds_read_b64_tr_b16 v[164:165], v183 offset:12288
	ds_read_b64_tr_b16 v[166:167], v183 offset:14336
	ds_read_b64_tr_b16 v[168:169], v184 offset:12288
	ds_read_b64_tr_b16 v[170:171], v184 offset:14336
	ds_read_b64_tr_b16 v[172:173], v185 offset:12288
	ds_read_b64_tr_b16 v[174:175], v185 offset:14336
	s_mov_b32 m0, s48
	s_nop 0
	global_load_lds_dwordx4 v8, s[24:25]
	global_load_lds_dwordx4 v9, s[24:25] offset:1024
	global_load_lds_dwordx4 v10, s[24:25] offset:2048
	global_load_lds_dwordx4 v11, s[24:25] offset:3072
	s_waitcnt lgkmcnt(0)
	v_mfma_f32_16x16x32_bf16 v[128:131], v[160:163], v[124:127], v[128:131]
	v_mfma_f32_16x16x32_bf16 v[132:135], v[164:167], v[124:127], v[132:135]
	v_mfma_f32_16x16x32_bf16 v[136:139], v[168:171], v[124:127], v[136:139]
	v_mfma_f32_16x16x32_bf16 v[140:143], v[172:175], v[124:127], v[140:143]
	s_nop 7
	s_nop 3
	v_mul_f32_e32 v128, v208, v128
	v_mul_f32_e32 v129, v208, v129
	v_mul_f32_e32 v130, v208, v130
	v_mul_f32_e32 v131, v208, v131
	v_cvt_pk_bf16_f32 v200, v128, v129
	v_cvt_pk_bf16_f32 v201, v130, v131
	v_mul_f32_e32 v132, v208, v132
	v_mul_f32_e32 v133, v208, v133
	v_mul_f32_e32 v134, v208, v134
	v_mul_f32_e32 v135, v208, v135
	v_cvt_pk_bf16_f32 v202, v132, v133
	v_cvt_pk_bf16_f32 v203, v134, v135
	v_mul_f32_e32 v136, v208, v136
	v_mul_f32_e32 v137, v208, v137
	v_mul_f32_e32 v138, v208, v138
	v_mul_f32_e32 v139, v208, v139
	v_cvt_pk_bf16_f32 v204, v136, v137
	v_cvt_pk_bf16_f32 v205, v138, v139
	v_mul_f32_e32 v140, v208, v140
	v_mul_f32_e32 v141, v208, v141
	v_mul_f32_e32 v142, v208, v142
	v_mul_f32_e32 v143, v208, v143
	v_cvt_pk_bf16_f32 v206, v140, v141
	v_cvt_pk_bf16_f32 v207, v142, v143
	s_mov_b64 exec, s[42:43]
	global_store_dwordx2 v190, v[200:201], s[34:35] offset:0 nt
	global_store_dwordx2 v190, v[202:203], s[34:35] offset:32 nt
	global_store_dwordx2 v190, v[204:205], s[34:35] offset:64 nt
	global_store_dwordx2 v190, v[206:207], s[34:35] offset:96 nt
	s_mov_b64 exec, -1
	s_waitcnt vmcnt(12)
	ds_read_b128 v[160:163], v180 offset:0
	ds_read_b128 v[164:167], v181 offset:0
	ds_read_b128 v[168:171], v180 offset:2048
	ds_read_b128 v[172:175], v181 offset:2048
	s_add_i32 s50, s2, s4
	s_cmp_lg_u32 s5, 0
	s_cbranch_scc1 .Lattn_nq_7
	s_cmp_lt_i32 s50, 0x8000
	s_cbranch_scc1 .Lattn_nq_7
	s_lshl_b32 s6, s57, 1
	s_add_i32 s6, s6, s56
	s_add_i32 s6, s6, 0x8000
	s_cmp_lt_u32 s56, 2
	s_cselect_b32 s6, s6, 0x10000
	s_cmp_ge_i32 s2, 0x8000
	s_cselect_b32 s50, 0x10000, s6

; __device__ __forceinline__ void phase_attn(KP kp, int l, unsigned char* shm) {
;     ...
;         for (int hb = 0; hb < 2; ++hb) {
;           bf16x8 ka[8][2];
;           if (kvh == 1 && hb == 0) {
; #pragma unroll
;             for (int k8 = 0; k8 < 8; ++k8) { ka[k8][0] = kpre[k8][0]; ka[k8][1] = kpre[k8][1]; }
;           } else {
; #pragma unroll
;             for (int k8 = 0; k8 < 8; ++k8) {
;               const int idx = selw[(hb * 8 + k8) * 16 + nn];
;               const bf16_t* kp = kbase + (size_t)idx * 128 + kvh * 64 + kg * 8;
;               ka[k8][0] = *(const bf16x8*)kp;
;               ka[k8][1] = *(const bf16x8*)(kp + 32);
;             }
;           }
;           __builtin_amdgcn_sched_barrier(0);
; #pragma unroll
;           for (int k8 = 0; k8 < 8; ++k8) {
;             f32x4 a = (f32x4){0.f, 0.f, 0.f, 0.f};
;             a = __builtin_amdgcn_mfma_f32_16x16x32_bf16(ka[k8][0], bq0, a, 0, 0, 0);
;             a = __builtin_amdgcn_mfma_f32_16x16x32_bf16(ka[k8][1], bq1, a, 0, 0, 0);
;             lg[hb * 8 + k8] = a;
;           }
;           __builtin_amdgcn_sched_barrier(0);
;         }
;       }
;       u32x4 vr[32];
; #pragma unroll
;       for (int i = 0; i < 16; ++i) {
;         const int idx = selw[i * 8 + ks8];
;         vr[i] = *(const u32x4*)(vbase + (size_t)idx * 128 + kvh * 64 + dc * 8);
;       }
;       float mx = -1e30f;
; #pragma unroll
;       for (int kb = 0; kb < 16; ++kb)
; #pragma unroll
;         for (int j = 0; j < 4; ++j) {
;           const int key = kb * 16 + kg * 4 + j;
;           lg[kb][j] = key < cnt ? lg[kb][j] : -1e30f;
;           mx = fmaxf(mx, lg[kb][j]);
;         }
.Lattn_join_10:
	s_add_u32 s28, s0, s7
	s_addc_u32 s29, s1, 0
	s_add_u32 s30, s0, s8
	s_addc_u32 s31, s1, 0
	s_lshl_b32 s6, s51, 9
	s_add_u32 s6, s6, 0x1b3c2000
	s_add_u32 s38, s0, s6
	s_addc_u32 s39, s1, 0
	s_lshl_b32 s6, s51, 10
	s_add_u32 s7, s6, 0x7ac0000
	s_add_u32 s40, s0, s7
	s_addc_u32 s41, s1, 0
	s_add_u32 s7, s6, 0x1c402000
	s_add_u32 s36, s0, s7
	s_addc_u32 s37, s1, 0
	global_load_dwordx2 v[198:199], v188, s[38:39] nt
	s_mov_b32 m0, s49
	s_nop 0
	global_load_lds_dwordx4 v12, s[24:25]
	global_load_lds_dwordx4 v13, s[24:25] offset:1024
	global_load_lds_dwordx4 v14, s[24:25] offset:2048
	global_load_lds_dwordx4 v15, s[24:25] offset:3072
	s_waitcnt lgkmcnt(0)
	v_mfma_f32_16x16x32_bf16 v[32:35], v[160:163], v[152:155], 0
	v_mfma_f32_16x16x32_bf16 v[36:39], v[168:171], v[152:155], 0
	v_mfma_f32_16x16x32_bf16 v[32:35], v[164:167], v[156:159], v[32:35]
	v_mfma_f32_16x16x32_bf16 v[36:39], v[172:175], v[156:159], v[36:39]
	s_waitcnt vmcnt(13)
	ds_read_b128 v[160:163], v180 offset:4096
	ds_read_b128 v[164:167], v181 offset:4096
	ds_read_b128 v[168:171], v180 offset:6144
	ds_read_b128 v[172:175], v181 offset:6144
	s_mov_b32 m0, s46
	s_nop 0
	global_load_lds_dwordx4 v16, s[24:25]
	global_load_lds_dwordx4 v18, s[24:25] offset:1024
	global_load_lds_dwordx4 v19, s[24:25] offset:2048
	global_load_lds_dwordx4 v20, s[24:25] offset:3072
	s_waitcnt lgkmcnt(0)
	v_mfma_f32_16x16x32_bf16 v[40:43], v[160:163], v[152:155], 0
	v_mfma_f32_16x16x32_bf16 v[44:47], v[168:171], v[152:155], 0
	v_mfma_f32_16x16x32_bf16 v[40:43], v[164:167], v[156:159], v[40:43]
	v_mfma_f32_16x16x32_bf16 v[44:47], v[172:175], v[156:159], v[44:47]
	s_waitcnt vmcnt(13)
	ds_read_b128 v[160:163], v180 offset:8192
	ds_read_b128 v[164:167], v181 offset:8192
	ds_read_b128 v[168:171], v180 offset:10240
	ds_read_b128 v[172:175], v181 offset:10240
	s_mov_b32 m0, s47
	s_nop 0
	global_load_lds_dwordx4 v21, s[24:25]
	global_load_lds_dwordx4 v22, s[24:25] offset:1024
	global_load_lds_dwordx4 v23, s[24:25] offset:2048
	global_load_lds_dwordx4 v24, s[24:25] offset:3072
	s_waitcnt lgkmcnt(0)
	v_mfma_f32_16x16x32_bf16 v[48:51], v[160:163], v[152:155], 0
	v_mfma_f32_16x16x32_bf16 v[52:55], v[168:171], v[152:155], 0
	v_mfma_f32_16x16x32_bf16 v[48:51], v[164:167], v[156:159], v[48:51]
	v_mfma_f32_16x16x32_bf16 v[52:55], v[172:175], v[156:159], v[52:55]
	s_waitcnt vmcnt(8)
	ds_read_b128 v[160:163], v180 offset:12288
	ds_read_b128 v[164:167], v181 offset:12288
	ds_read_b128 v[168:171], v180 offset:14336
	ds_read_b128 v[172:175], v181 offset:14336
	s_mov_b32 m0, s48
	s_nop 0
	global_load_lds_dwordx4 v25, s[24:25]
	global_load_lds_dwordx4 v26, s[24:25] offset:1024
	global_load_lds_dwordx4 v27, s[24:25] offset:2048
	global_load_lds_dwordx4 v28, s[24:25] offset:3072
	s_waitcnt lgkmcnt(0)
	v_mfma_f32_16x16x32_bf16 v[56:59], v[160:163], v[152:155], 0
	v_mfma_f32_16x16x32_bf16 v[60:63], v[168:171], v[152:155], 0
	v_mfma_f32_16x16x32_bf16 v[56:59], v[164:167], v[156:159], v[56:59]
	v_mfma_f32_16x16x32_bf16 v[60:63], v[172:175], v[156:159], v[60:63]
	s_waitcnt vmcnt(8)
	ds_read_b128 v[160:163], v180 offset:0
	ds_read_b128 v[164:167], v181 offset:0
	ds_read_b128 v[168:171], v180 offset:2048
	ds_read_b128 v[172:175], v181 offset:2048
	s_mov_b32 m0, s49
	s_nop 0
	global_load_lds_dwordx4 v29, s[24:25]
	global_load_lds_dwordx4 v30, s[24:25] offset:1024
	global_load_lds_dwordx4 v31, s[24:25] offset:2048
	global_load_lds_dwordx4 v219, s[24:25] offset:3072
	s_waitcnt lgkmcnt(0)
	v_mfma_f32_16x16x32_bf16 v[64:67], v[160:163], v[152:155], 0
	v_mfma_f32_16x16x32_bf16 v[68:71], v[168:171], v[152:155], 0
	v_mfma_f32_16x16x32_bf16 v[64:67], v[164:167], v[156:159], v[64:67]
	v_mfma_f32_16x16x32_bf16 v[68:71], v[172:175], v[156:159], v[68:71]
	s_waitcnt vmcnt(8)
	ds_read_b128 v[160:163], v180 offset:4096
	ds_read_b128 v[164:167], v181 offset:4096
	ds_read_b128 v[168:171], v180 offset:6144
	ds_read_b128 v[172:175], v181 offset:6144
	s_mov_b32 m0, s46
	s_nop 0
	global_load_lds_dwordx4 v0, s[26:27]
	global_load_lds_dwordx4 v1, s[26:27] offset:1024
	global_load_lds_dwordx4 v2, s[26:27] offset:2048
	global_load_lds_dwordx4 v3, s[26:27] offset:3072
	s_waitcnt lgkmcnt(0)
	v_mfma_f32_16x16x32_bf16 v[72:75], v[160:163], v[152:155], 0
	v_mfma_f32_16x16x32_bf16 v[76:79], v[168:171], v[152:155], 0
	v_mfma_f32_16x16x32_bf16 v[72:75], v[164:167], v[156:159], v[72:75]
	v_mfma_f32_16x16x32_bf16 v[76:79], v[172:175], v[156:159], v[76:79]
	s_waitcnt vmcnt(8)
	ds_read_b128 v[160:163], v180 offset:8192
	ds_read_b128 v[164:167], v181 offset:8192
	ds_read_b128 v[168:171], v180 offset:10240
	ds_read_b128 v[172:175], v181 offset:10240
	s_mov_b32 m0, s47
	s_nop 0
	global_load_lds_dwordx4 v4, s[26:27]
	global_load_lds_dwordx4 v5, s[26:27] offset:1024
	global_load_lds_dwordx4 v6, s[26:27] offset:2048
	global_load_lds_dwordx4 v7, s[26:27] offset:3072
	s_waitcnt lgkmcnt(0)
	v_mfma_f32_16x16x32_bf16 v[80:83], v[160:163], v[152:155], 0
	v_mfma_f32_16x16x32_bf16 v[84:87], v[168:171], v[152:155], 0
	v_mfma_f32_16x16x32_bf16 v[80:83], v[164:167], v[156:159], v[80:83]
	v_mfma_f32_16x16x32_bf16 v[84:87], v[172:175], v[156:159], v[84:87]
	s_waitcnt vmcnt(8)
	ds_read_b128 v[160:163], v180 offset:12288
	ds_read_b128 v[164:167], v181 offset:12288
	ds_read_b128 v[168:171], v180 offset:14336
	ds_read_b128 v[172:175], v181 offset:14336
	s_mov_b32 m0, s48
	s_nop 0
	global_load_lds_dwordx4 v8, s[26:27]
	global_load_lds_dwordx4 v9, s[26:27] offset:1024
	global_load_lds_dwordx4 v10, s[26:27] offset:2048
	global_load_lds_dwordx4 v11, s[26:27] offset:3072
	s_waitcnt lgkmcnt(0)
	v_mfma_f32_16x16x32_bf16 v[88:91], v[160:163], v[152:155], 0
	v_mfma_f32_16x16x32_bf16 v[92:95], v[168:171], v[152:155], 0
	v_mfma_f32_16x16x32_bf16 v[88:91], v[164:167], v[156:159], v[88:91]
	v_mfma_f32_16x16x32_bf16 v[92:95], v[172:175], v[156:159], v[92:95]
	s_nop 7
	s_nop 3
	s_cmp_ge_u32 s44, 0x100
	s_cbranch_scc1 .Lattn_nomask_11
	s_cmp_ge_u32 s44, 0xc0
	s_cbranch_scc1 .Lattn_m192_12
	s_cmp_ge_u32 s44, 0x80
	s_cbranch_scc1 .Lattn_m128_13
	v_mov_b32_e32 v48, 0xf149f2ca
	v_mov_b32_e32 v49, 0xf149f2ca
	v_mov_b32_e32 v50, 0xf149f2ca
	v_mov_b32_e32 v51, 0xf149f2ca
	v_mov_b32_e32 v52, 0xf149f2ca
	v_mov_b32_e32 v53, 0xf149f2ca
	v_mov_b32_e32 v54, 0xf149f2ca
	v_mov_b32_e32 v55, 0xf149f2ca
	v_mov_b32_e32 v56, 0xf149f2ca
	v_mov_b32_e32 v57, 0xf149f2ca
	v_mov_b32_e32 v58, 0xf149f2ca
	v_mov_b32_e32 v59, 0xf149f2ca
	v_mov_b32_e32 v60, 0xf149f2ca
	v_mov_b32_e32 v61, 0xf149f2ca
	v_mov_b32_e32 v62, 0xf149f2ca
	v_mov_b32_e32 v63, 0xf149f2ca

; __device__ __forceinline__ void phase_attn(KP kp, int l, unsigned char* shm) {
;     ...
;       float mx = -1e30f;
; #pragma unroll
;       for (int kb = 0; kb < 16; ++kb)
; #pragma unroll
;         for (int j = 0; j < 4; ++j) {
;           const int key = kb * 16 + kg * 4 + j;
;           lg[kb][j] = key < cnt ? lg[kb][j] : -1e30f;
;           mx = fmaxf(mx, lg[kb][j]);
;         }
;       mx = fmaxf(mx, __shfl_xor(mx, 16));
;       mx = fmaxf(mx, __shfl_xor(mx, 32));
;       float sum = 0.f;
; #pragma unroll
;       for (int kb = 0; kb < 16; ++kb)
; #pragma unroll
;         for (int j = 0; j < 4; ++j) { lg[kb][j] = __builtin_amdgcn_exp2f(lg[kb][j] - mx); sum += lg[kb][j]; }
.Lattn_nomask_11:
	v_max3_f32 v176, v32, v33, v34
	v_max3_f32 v176, v176, v35, v36
	v_max3_f32 v176, v176, v37, v38
	v_max3_f32 v176, v176, v39, v40
	v_max3_f32 v176, v176, v41, v42
	v_max3_f32 v176, v176, v43, v44
	v_max3_f32 v176, v176, v45, v46
	v_max3_f32 v176, v176, v47, v48
	v_max3_f32 v176, v176, v49, v50
	v_max3_f32 v176, v176, v51, v52
	v_max3_f32 v176, v176, v53, v54
	v_max3_f32 v176, v176, v55, v56
	v_max3_f32 v176, v176, v57, v58
	v_max3_f32 v176, v176, v59, v60
	v_max3_f32 v176, v176, v61, v62
	v_max3_f32 v176, v176, v63, v64
	v_max3_f32 v176, v176, v65, v66
	v_max3_f32 v176, v176, v67, v68
	v_max3_f32 v176, v176, v69, v70
	v_max3_f32 v176, v176, v71, v72
	v_max3_f32 v176, v176, v73, v74
	v_max3_f32 v176, v176, v75, v76
	v_max3_f32 v176, v176, v77, v78
	v_max3_f32 v176, v176, v79, v80
	v_max3_f32 v176, v176, v81, v82
	v_max3_f32 v176, v176, v83, v84
	v_max3_f32 v176, v176, v85, v86
	v_max3_f32 v176, v176, v87, v88
	v_max3_f32 v176, v176, v89, v90
	v_max3_f32 v176, v176, v91, v92
	v_max3_f32 v176, v176, v93, v94
	v_max_f32_e32 v176, v176, v95
	ds_bpermute_b32 v197, v191, v176
	s_waitcnt lgkmcnt(0)
	v_max_f32_e32 v176, v176, v197
	ds_bpermute_b32 v197, v192, v176
	s_waitcnt lgkmcnt(0)
	v_max_f32_e32 v176, v176, v197
	v_mov_b32_e32 v177, v176
	v_pk_add_f32 v[32:33], v[32:33], v[176:177] neg_lo:[0,1] neg_hi:[0,1]
	v_pk_add_f32 v[34:35], v[34:35], v[176:177] neg_lo:[0,1] neg_hi:[0,1]
	v_pk_add_f32 v[36:37], v[36:37], v[176:177] neg_lo:[0,1] neg_hi:[0,1]
	v_pk_add_f32 v[38:39], v[38:39], v[176:177] neg_lo:[0,1] neg_hi:[0,1]
	v_pk_add_f32 v[40:41], v[40:41], v[176:177] neg_lo:[0,1] neg_hi:[0,1]
	v_pk_add_f32 v[42:43], v[42:43], v[176:177] neg_lo:[0,1] neg_hi:[0,1]
	v_pk_add_f32 v[44:45], v[44:45], v[176:177] neg_lo:[0,1] neg_hi:[0,1]
	v_pk_add_f32 v[46:47], v[46:47], v[176:177] neg_lo:[0,1] neg_hi:[0,1]
	v_pk_add_f32 v[48:49], v[48:49], v[176:177] neg_lo:[0,1] neg_hi:[0,1]
	v_pk_add_f32 v[50:51], v[50:51], v[176:177] neg_lo:[0,1] neg_hi:[0,1]
	v_pk_add_f32 v[52:53], v[52:53], v[176:177] neg_lo:[0,1] neg_hi:[0,1]
	v_pk_add_f32 v[54:55], v[54:55], v[176:177] neg_lo:[0,1] neg_hi:[0,1]
	v_pk_add_f32 v[56:57], v[56:57], v[176:177] neg_lo:[0,1] neg_hi:[0,1]
	v_pk_add_f32 v[58:59], v[58:59], v[176:177] neg_lo:[0,1] neg_hi:[0,1]
	v_pk_add_f32 v[60:61], v[60:61], v[176:177] neg_lo:[0,1] neg_hi:[0,1]
	v_pk_add_f32 v[62:63], v[62:63], v[176:177] neg_lo:[0,1] neg_hi:[0,1]
	v_pk_add_f32 v[64:65], v[64:65], v[176:177] neg_lo:[0,1] neg_hi:[0,1]
	v_pk_add_f32 v[66:67], v[66:67], v[176:177] neg_lo:[0,1] neg_hi:[0,1]
	v_pk_add_f32 v[68:69], v[68:69], v[176:177] neg_lo:[0,1] neg_hi:[0,1]
	v_pk_add_f32 v[70:71], v[70:71], v[176:177] neg_lo:[0,1] neg_hi:[0,1]
	v_pk_add_f32 v[72:73], v[72:73], v[176:177] neg_lo:[0,1] neg_hi:[0,1]
	v_pk_add_f32 v[74:75], v[74:75], v[176:177] neg_lo:[0,1] neg_hi:[0,1]
	v_pk_add_f32 v[76:77], v[76:77], v[176:177] neg_lo:[0,1] neg_hi:[0,1]
	v_pk_add_f32 v[78:79], v[78:79], v[176:177] neg_lo:[0,1] neg_hi:[0,1]
	v_pk_add_f32 v[80:81], v[80:81], v[176:177] neg_lo:[0,1] neg_hi:[0,1]
	v_pk_add_f32 v[82:83], v[82:83], v[176:177] neg_lo:[0,1] neg_hi:[0,1]
	v_pk_add_f32 v[84:85], v[84:85], v[176:177] neg_lo:[0,1] neg_hi:[0,1]
	v_pk_add_f32 v[86:87], v[86:87], v[176:177] neg_lo:[0,1] neg_hi:[0,1]
	v_pk_add_f32 v[88:89], v[88:89], v[176:177] neg_lo:[0,1] neg_hi:[0,1]
	v_pk_add_f32 v[90:91], v[90:91], v[176:177] neg_lo:[0,1] neg_hi:[0,1]
	v_pk_add_f32 v[92:93], v[92:93], v[176:177] neg_lo:[0,1] neg_hi:[0,1]
	v_pk_add_f32 v[94:95], v[94:95], v[176:177] neg_lo:[0,1] neg_hi:[0,1]
	v_exp_f32_e32 v32, v32
	v_exp_f32_e32 v33, v33
	v_exp_f32_e32 v34, v34
	v_exp_f32_e32 v35, v35
	v_exp_f32_e32 v36, v36
	v_exp_f32_e32 v37, v37
	v_pk_add_f32 v[178:179], v[32:33], v[34:35]
	v_exp_f32_e32 v38, v38
	v_exp_f32_e32 v39, v39
	v_pk_add_f32 v[178:179], v[178:179], v[36:37]
	v_exp_f32_e32 v40, v40
	v_exp_f32_e32 v41, v41
	v_pk_add_f32 v[178:179], v[178:179], v[38:39]
	v_exp_f32_e32 v42, v42
	v_exp_f32_e32 v43, v43
	v_pk_add_f32 v[178:179], v[178:179], v[40:41]
	v_exp_f32_e32 v44, v44
	v_exp_f32_e32 v45, v45
	v_pk_add_f32 v[178:179], v[178:179], v[42:43]
	v_exp_f32_e32 v46, v46
	v_exp_f32_e32 v47, v47
	v_pk_add_f32 v[178:179], v[178:179], v[44:45]
	v_exp_f32_e32 v48, v48
	v_exp_f32_e32 v49, v49
	v_pk_add_f32 v[178:179], v[178:179], v[46:47]
	v_exp_f32_e32 v50, v50
	v_exp_f32_e32 v51, v51
	v_pk_add_f32 v[178:179], v[178:179], v[48:49]
	v_exp_f32_e32 v52, v52
	v_exp_f32_e32 v53, v53
	v_pk_add_f32 v[178:179], v[178:179], v[50:51]
	v_exp_f32_e32 v54, v54
	v_exp_f32_e32 v55, v55
	v_pk_add_f32 v[178:179], v[178:179], v[52:53]
	v_exp_f32_e32 v56, v56
	v_exp_f32_e32 v57, v57
	v_pk_add_f32 v[178:179], v[178:179], v[54:55]
	v_exp_f32_e32 v58, v58
	v_exp_f32_e32 v59, v59
	v_pk_add_f32 v[178:179], v[178:179], v[56:57]
	v_exp_f32_e32 v60, v60
	v_exp_f32_e32 v61, v61
	v_pk_add_f32 v[178:179], v[178:179], v[58:59]
	v_exp_f32_e32 v62, v62
	v_exp_f32_e32 v63, v63
	v_pk_add_f32 v[178:179], v[178:179], v[60:61]
	v_exp_f32_e32 v64, v64
	v_exp_f32_e32 v65, v65
	v_pk_add_f32 v[178:179], v[178:179], v[62:63]
	v_exp_f32_e32 v66, v66
	v_exp_f32_e32 v67, v67
	v_pk_add_f32 v[178:179], v[178:179], v[64:65]
	v_exp_f32_e32 v68, v68
	v_exp_f32_e32 v69, v69
	v_pk_add_f32 v[178:179], v[178:179], v[66:67]
	v_exp_f32_e32 v70, v70
	v_exp_f32_e32 v71, v71
	v_pk_add_f32 v[178:179], v[178:179], v[68:69]
	v_exp_f32_e32 v72, v72
	v_exp_f32_e32 v73, v73
	v_pk_add_f32 v[178:179], v[178:179], v[70:71]
	v_exp_f32_e32 v74, v74
	v_exp_f32_e32 v75, v75
	v_pk_add_f32 v[178:179], v[178:179], v[72:73]
	v_exp_f32_e32 v76, v76
	v_exp_f32_e32 v77, v77
	v_pk_add_f32 v[178:179], v[178:179], v[74:75]
; __device__ __forceinline__ void phase_attn(KP kp, int l, unsigned char* shm) {
;     ...
;       float sum = 0.f;
; #pragma unroll
;       for (int kb = 0; kb < 16; ++kb)
; #pragma unroll
;         for (int j = 0; j < 4; ++j) { lg[kb][j] = __builtin_amdgcn_exp2f(lg[kb][j] - mx); sum += lg[kb][j]; }
;       sum += __shfl_xor(sum, 16);
;       sum += __shfl_xor(sum, 32);
;       const float inv = 1.f / sum;
;       bf16x8 pf[8];
; #pragma unroll
;       for (int s8 = 0; s8 < 8; ++s8) {
;         u32x4 pk;
;         pk[0] = cvt_pk_bf16(lg[2 * s8][0], lg[2 * s8][1]);
;         pk[1] = cvt_pk_bf16(lg[2 * s8][2], lg[2 * s8][3]);
;         pk[2] = cvt_pk_bf16(lg[2 * s8 + 1][0], lg[2 * s8 + 1][1]);
;         pk[3] = cvt_pk_bf16(lg[2 * s8 + 1][2], lg[2 * s8 + 1][3]);
;         pf[s8] = __builtin_bit_cast(bf16x8, pk);
;       }
;       f32x4 oacc[4];
; #pragma unroll
;       for (int c = 0; c < 4; ++c) oacc[c] = (f32x4){0.f, 0.f, 0.f, 0.f};
;       for (int repV = 0; repV < ((PROBE & 256) ? 2 : 1); ++repV)
;       {
;         if (repV) {
; #pragma unroll
;           for (int c = 0; c < 4; ++c) oacc[c] = (f32x4){0.f, 0.f, 0.f, 0.f};
;         }
; #pragma unroll
;         for (int i = 16; i < 32; ++i) {
;           const int idx = selw[i * 8 + ks8];
;           vr[i] = *(const u32x4*)(vbase + (size_t)idx * 128 + kvh * 64 + dc * 8);
;         }
; #pragma unroll
;         for (int s8 = 0; s8 < 8; ++s8) {
; #pragma unroll
;           for (int it = 0; it < 4; ++it) *(u32x4*)(tileb + (it * 8 + ks8) * 144 + dc * 16) = vr[s8 * 4 + it];
;           u32x2 t0, t1, t2, t3, t4, t5, t6, t7;
;           asm volatile(
;               "ds_read_b64_tr_b16 %0, %8\n\tds_read_b64_tr_b16 %1, %8 offset:2304\n\t"
;               "ds_read_b64_tr_b16 %2, %8 offset:32\n\tds_read_b64_tr_b16 %3, %8 offset:2336\n\t"
;               "ds_read_b64_tr_b16 %4, %8 offset:64\n\tds_read_b64_tr_b16 %5, %8 offset:2368\n\t"
;               "ds_read_b64_tr_b16 %6, %8 offset:96\n\tds_read_b64_tr_b16 %7, %8 offset:2400\n\t"
;               "s_waitcnt lgkmcnt(0)"
;               : "=&v"(t0), "=&v"(t1), "=&v"(t2), "=&v"(t3), "=&v"(t4), "=&v"(t5), "=&v"(t6), "=&v"(t7)
;               : "v"(tr_addr)
;               : "memory");
;           const bf16x8 a0 = __builtin_bit_cast(bf16x8, (u32x4){t0[0], t0[1], t1[0], t1[1]});
;           const bf16x8 a1 = __builtin_bit_cast(bf16x8, (u32x4){t2[0], t2[1], t3[0], t3[1]});
	v_exp_f32_e32 v78, v78
	v_exp_f32_e32 v79, v79
	v_pk_add_f32 v[178:179], v[178:179], v[76:77]
	v_exp_f32_e32 v80, v80
	v_exp_f32_e32 v81, v81
	v_pk_add_f32 v[178:179], v[178:179], v[78:79]
	v_exp_f32_e32 v82, v82
	v_exp_f32_e32 v83, v83
	v_pk_add_f32 v[178:179], v[178:179], v[80:81]
	v_exp_f32_e32 v84, v84
	v_exp_f32_e32 v85, v85
	v_pk_add_f32 v[178:179], v[178:179], v[82:83]
	v_exp_f32_e32 v86, v86
	v_exp_f32_e32 v87, v87
	v_pk_add_f32 v[178:179], v[178:179], v[84:85]
	v_exp_f32_e32 v88, v88
	v_exp_f32_e32 v89, v89
	v_pk_add_f32 v[178:179], v[178:179], v[86:87]
	v_exp_f32_e32 v90, v90
	v_exp_f32_e32 v91, v91
	v_pk_add_f32 v[178:179], v[178:179], v[88:89]
	v_exp_f32_e32 v92, v92
	v_exp_f32_e32 v93, v93
	v_pk_add_f32 v[178:179], v[178:179], v[90:91]
	v_exp_f32_e32 v94, v94
	v_exp_f32_e32 v95, v95
	v_pk_add_f32 v[178:179], v[178:179], v[92:93]
	s_nop 0
	v_pk_add_f32 v[178:179], v[178:179], v[94:95]
	v_add_f32_e32 v210, v178, v179
	ds_bpermute_b32 v197, v191, v210
	v_cvt_pk_bf16_f32 v96, v32, v33
	v_cvt_pk_bf16_f32 v97, v34, v35
	v_cvt_pk_bf16_f32 v98, v36, v37
	v_cvt_pk_bf16_f32 v99, v38, v39
	v_cvt_pk_bf16_f32 v100, v40, v41
	v_cvt_pk_bf16_f32 v101, v42, v43
	v_cvt_pk_bf16_f32 v102, v44, v45
	v_cvt_pk_bf16_f32 v103, v46, v47
	v_cvt_pk_bf16_f32 v104, v48, v49
	v_cvt_pk_bf16_f32 v105, v50, v51
	v_cvt_pk_bf16_f32 v106, v52, v53
	v_cvt_pk_bf16_f32 v107, v54, v55
	v_cvt_pk_bf16_f32 v108, v56, v57
	v_cvt_pk_bf16_f32 v109, v58, v59
	v_cvt_pk_bf16_f32 v110, v60, v61
	v_cvt_pk_bf16_f32 v111, v62, v63
	s_waitcnt lgkmcnt(0)
	v_add_f32_e32 v210, v210, v197
	ds_bpermute_b32 v197, v192, v210
	v_cvt_pk_bf16_f32 v112, v64, v65
	v_cvt_pk_bf16_f32 v113, v66, v67
	v_cvt_pk_bf16_f32 v114, v68, v69
	v_cvt_pk_bf16_f32 v115, v70, v71
	v_cvt_pk_bf16_f32 v116, v72, v73
	v_cvt_pk_bf16_f32 v117, v74, v75
	v_cvt_pk_bf16_f32 v118, v76, v77
	v_cvt_pk_bf16_f32 v119, v78, v79
	v_cvt_pk_bf16_f32 v120, v80, v81
	v_cvt_pk_bf16_f32 v121, v82, v83
	v_cvt_pk_bf16_f32 v122, v84, v85
	v_cvt_pk_bf16_f32 v123, v86, v87
	v_cvt_pk_bf16_f32 v124, v88, v89
	v_cvt_pk_bf16_f32 v125, v90, v91
	v_cvt_pk_bf16_f32 v126, v92, v93
	v_cvt_pk_bf16_f32 v127, v94, v95
	s_waitcnt lgkmcnt(0)
	v_add_f32_e32 v210, v210, v197
	v_rcp_f32_e32 v208, v210
	s_waitcnt vmcnt(8)
	ds_read_b64_tr_b16 v[160:161], v182 offset:0
	ds_read_b64_tr_b16 v[162:163], v182 offset:2048
	ds_read_b64_tr_b16 v[164:165], v183 offset:0
	ds_read_b64_tr_b16 v[166:167], v183 offset:2048
	ds_read_b64_tr_b16 v[168:169], v184 offset:0
	ds_read_b64_tr_b16 v[170:171], v184 offset:2048
	ds_read_b64_tr_b16 v[172:173], v185 offset:0
	ds_read_b64_tr_b16 v[174:175], v185 offset:2048
	s_mov_b64 exec, s[42:43]
	global_load_dwordx4 v[144:147], v189, s[40:41] nt
	global_load_dwordx4 v[148:151], v189, s[40:41] offset:64 nt
	global_load_dwordx4 v[152:155], v189, s[40:41] offset:512 nt
	global_load_dwordx4 v[156:159], v189, s[40:41] offset:576 nt
	s_mov_b64 exec, -1
	s_mov_b32 m0, s49
	s_nop 0
	global_load_lds_dwordx4 v12, s[26:27]
	global_load_lds_dwordx4 v13, s[26:27] offset:1024
	global_load_lds_dwordx4 v14, s[26:27] offset:2048
	global_load_lds_dwordx4 v15, s[26:27] offset:3072
	s_waitcnt lgkmcnt(0)
	v_mfma_f32_16x16x32_bf16 v[128:131], v[160:163], v[96:99], 0
	v_mfma_f32_16x16x32_bf16 v[132:135], v[164:167], v[96:99], 0
	v_mfma_f32_16x16x32_bf16 v[136:139], v[168:171], v[96:99], 0
	v_mfma_f32_16x16x32_bf16 v[140:143], v[172:175], v[96:99], 0
	s_waitcnt vmcnt(12)
	ds_read_b64_tr_b16 v[160:161], v182 offset:4096
	ds_read_b64_tr_b16 v[162:163], v182 offset:6144
	ds_read_b64_tr_b16 v[164:165], v183 offset:4096
	ds_read_b64_tr_b16 v[166:167], v183 offset:6144
	ds_read_b64_tr_b16 v[168:169], v184 offset:4096
	ds_read_b64_tr_b16 v[170:171], v184 offset:6144
	ds_read_b64_tr_b16 v[172:173], v185 offset:4096
	ds_read_b64_tr_b16 v[174:175], v185 offset:6144
	s_mov_b32 m0, s46
	s_nop 0
	global_load_lds_dwordx4 v16, s[26:27]
	global_load_lds_dwordx4 v18, s[26:27] offset:1024
	global_load_lds_dwordx4 v19, s[26:27] offset:2048
	global_load_lds_dwordx4 v20, s[26:27] offset:3072
	s_waitcnt lgkmcnt(0)
	v_mfma_f32_16x16x32_bf16 v[128:131], v[160:163], v[100:103], v[128:131]
	v_mfma_f32_16x16x32_bf16 v[132:135], v[164:167], v[100:103], v[132:135]
	v_mfma_f32_16x16x32_bf16 v[136:139], v[168:171], v[100:103], v[136:139]
	v_mfma_f32_16x16x32_bf16 v[140:143], v[172:175], v[100:103], v[140:143]
	s_waitcnt vmcnt(12)
	ds_read_b64_tr_b16 v[160:161], v182 offset:8192
	ds_read_b64_tr_b16 v[162:163], v182 offset:10240
	ds_read_b64_tr_b16 v[164:165], v183 offset:8192
	ds_read_b64_tr_b16 v[166:167], v183 offset:10240
	ds_read_b64_tr_b16 v[168:169], v184 offset:8192
	ds_read_b64_tr_b16 v[170:171], v184 offset:10240
	ds_read_b64_tr_b16 v[172:173], v185 offset:8192
	ds_read_b64_tr_b16 v[174:175], v185 offset:10240
	s_mov_b32 m0, s47
	s_nop 0
	global_load_lds_dwordx4 v21, s[26:27]
	global_load_lds_dwordx4 v22, s[26:27] offset:1024
	global_load_lds_dwordx4 v23, s[26:27] offset:2048
	global_load_lds_dwordx4 v24, s[26:27] offset:3072
	s_waitcnt lgkmcnt(0)
	v_mfma_f32_16x16x32_bf16 v[128:131], v[160:163], v[104:107], v[128:131]
	v_mfma_f32_16x16x32_bf16 v[132:135], v[164:167], v[104:107], v[132:135]
	v_mfma_f32_16x16x32_bf16 v[136:139], v[168:171], v[104:107], v[136:139]
	v_mfma_f32_16x16x32_bf16 v[140:143], v[172:175], v[104:107], v[140:143]
	s_waitcnt vmcnt(8)
; __device__ __forceinline__ void phase_attn(KP kp, int l, unsigned char* shm) {
;     ...
;     const int cnt = n < 256 ? n : 256;
;     {
;       u32x2 sv = *(const u32x2*)(SEL + (size_t)r * 256 + lane * 4);
;       const int k0 = lane * 4;
;       unsigned a0 = sv[0] & 0xffffu, a1 = sv[0] >> 16, a2 = sv[1] & 0xffffu, a3 = sv[1] >> 16;
;       a0 = (k0 < cnt) ? a0 : 0u; a1 = (k0 + 1 < cnt) ? a1 : 0u; a2 = (k0 + 2 < cnt) ? a2 : 0u; a3 = (k0 + 3 < cnt) ? a3 : 0u;
;       u32x2 o;
;       o[0] = a0 | (a1 << 16); o[1] = a2 | (a3 << 16);
;       *(u32x2*)(selw + lane * 4) = o;
;     }
;     ...
;         for (int i = 16; i < 32; ++i) {
;           const int idx = selw[i * 8 + ks8];
;           vr[i] = *(const u32x4*)(vbase + (size_t)idx * 128 + kvh * 64 + dc * 8);
;         }
; #pragma unroll
;         for (int s8 = 0; s8 < 8; ++s8) {
; #pragma unroll
;           for (int it = 0; it < 4; ++it) *(u32x4*)(tileb + (it * 8 + ks8) * 144 + dc * 16) = vr[s8 * 4 + it];
;           u32x2 t0, t1, t2, t3, t4, t5, t6, t7;
;           asm volatile(
;               "ds_read_b64_tr_b16 %0, %8\n\tds_read_b64_tr_b16 %1, %8 offset:2304\n\t"
;               "ds_read_b64_tr_b16 %2, %8 offset:32\n\tds_read_b64_tr_b16 %3, %8 offset:2336\n\t"
;               "ds_read_b64_tr_b16 %4, %8 offset:64\n\tds_read_b64_tr_b16 %5, %8 offset:2368\n\t"
;               "ds_read_b64_tr_b16 %6, %8 offset:96\n\tds_read_b64_tr_b16 %7, %8 offset:2400\n\t"
;               "s_waitcnt lgkmcnt(0)"
;               : "=&v"(t0), "=&v"(t1), "=&v"(t2), "=&v"(t3), "=&v"(t4), "=&v"(t5), "=&v"(t6), "=&v"(t7)
;               : "v"(tr_addr)
;               : "memory");
;           const bf16x8 a0 = __builtin_bit_cast(bf16x8, (u32x4){t0[0], t0[1], t1[0], t1[1]});
;           const bf16x8 a1 = __builtin_bit_cast(bf16x8, (u32x4){t2[0], t2[1], t3[0], t3[1]});
;           const bf16x8 a2 = __builtin_bit_cast(bf16x8, (u32x4){t4[0], t4[1], t5[0], t5[1]});
;           const bf16x8 a3 = __builtin_bit_cast(bf16x8, (u32x4){t6[0], t6[1], t7[0], t7[1]});
;           oacc[0] = __builtin_amdgcn_mfma_f32_16x16x32_bf16(a0, pf[s8], oacc[0], 0, 0, 0);
;           oacc[1] = __builtin_amdgcn_mfma_f32_16x16x32_bf16(a1, pf[s8], oacc[1], 0, 0, 0);
;           oacc[2] = __builtin_amdgcn_mfma_f32_16x16x32_bf16(a2, pf[s8], oacc[2], 0, 0, 0);
;           oacc[3] = __builtin_amdgcn_mfma_f32_16x16x32_bf16(a3, pf[s8], oacc[3], 0, 0, 0);
	ds_read_b64_tr_b16 v[160:161], v182 offset:12288
	ds_read_b64_tr_b16 v[162:163], v182 offset:14336
	ds_read_b64_tr_b16 v[164:165], v183 offset:12288
	ds_read_b64_tr_b16 v[166:167], v183 offset:14336
	ds_read_b64_tr_b16 v[168:169], v184 offset:12288
	ds_read_b64_tr_b16 v[170:171], v184 offset:14336
	ds_read_b64_tr_b16 v[172:173], v185 offset:12288
	ds_read_b64_tr_b16 v[174:175], v185 offset:14336
	s_mov_b32 m0, s48
	s_nop 0
	global_load_lds_dwordx4 v25, s[26:27]
	global_load_lds_dwordx4 v26, s[26:27] offset:1024
	global_load_lds_dwordx4 v27, s[26:27] offset:2048
	global_load_lds_dwordx4 v28, s[26:27] offset:3072
	s_waitcnt lgkmcnt(0)
	v_mfma_f32_16x16x32_bf16 v[128:131], v[160:163], v[108:111], v[128:131]
	v_mfma_f32_16x16x32_bf16 v[132:135], v[164:167], v[108:111], v[132:135]
	v_mfma_f32_16x16x32_bf16 v[136:139], v[168:171], v[108:111], v[136:139]
	v_mfma_f32_16x16x32_bf16 v[140:143], v[172:175], v[108:111], v[140:143]
	s_waitcnt vmcnt(8)
	ds_read_b64_tr_b16 v[160:161], v182 offset:0
	ds_read_b64_tr_b16 v[162:163], v182 offset:2048
	ds_read_b64_tr_b16 v[164:165], v183 offset:0
	ds_read_b64_tr_b16 v[166:167], v183 offset:2048
	ds_read_b64_tr_b16 v[168:169], v184 offset:0
	ds_read_b64_tr_b16 v[170:171], v184 offset:2048
	ds_read_b64_tr_b16 v[172:173], v185 offset:0
	ds_read_b64_tr_b16 v[174:175], v185 offset:2048
	s_mov_b32 m0, s49
	s_nop 0
	global_load_lds_dwordx4 v29, s[26:27]
	global_load_lds_dwordx4 v30, s[26:27] offset:1024
	global_load_lds_dwordx4 v31, s[26:27] offset:2048
	global_load_lds_dwordx4 v219, s[26:27] offset:3072
	s_waitcnt lgkmcnt(0)
	v_mfma_f32_16x16x32_bf16 v[128:131], v[160:163], v[112:115], v[128:131]
	v_mfma_f32_16x16x32_bf16 v[132:135], v[164:167], v[112:115], v[132:135]
	v_mfma_f32_16x16x32_bf16 v[136:139], v[168:171], v[112:115], v[136:139]
	v_mfma_f32_16x16x32_bf16 v[140:143], v[172:175], v[112:115], v[140:143]
	s_lshr_b32 s6, s45, 2
	v_cmp_gt_u32_e32 vcc, s6, v252
	s_nop 1
	v_cndmask_b32_e32 v198, 0, v198, vcc
	v_cndmask_b32_e32 v199, 0, v199, vcc
	ds_write_b64 v186, v[198:199]
	ds_read_u16 v0, v187 offset:0
	ds_read_u16 v1, v187 offset:16
	ds_read_u16 v2, v187 offset:32
	ds_read_u16 v3, v187 offset:48
	ds_read_u16 v4, v187 offset:64
	ds_read_u16 v5, v187 offset:80
	ds_read_u16 v6, v187 offset:96
	ds_read_u16 v7, v187 offset:112
	s_waitcnt lgkmcnt(0)
	v_lshl_add_u32 v0, v0, 8, v193
	v_lshl_add_u32 v1, v1, 8, v194
	v_lshl_add_u32 v2, v2, 8, v195
	v_lshl_add_u32 v3, v3, 8, v196
	v_lshl_add_u32 v4, v4, 8, v193
	v_lshl_add_u32 v5, v5, 8, v194
	v_lshl_add_u32 v6, v6, 8, v195
	v_lshl_add_u32 v7, v7, 8, v196
	ds_read_u16 v8, v187 offset:128
	ds_read_u16 v9, v187 offset:144
	ds_read_u16 v10, v187 offset:160
	ds_read_u16 v11, v187 offset:176
	ds_read_u16 v12, v187 offset:192
	ds_read_u16 v13, v187 offset:208
	ds_read_u16 v14, v187 offset:224
	ds_read_u16 v15, v187 offset:240
	s_waitcnt lgkmcnt(0)
	v_lshl_add_u32 v8, v8, 8, v193
	v_lshl_add_u32 v9, v9, 8, v194
	v_lshl_add_u32 v10, v10, 8, v195
	v_lshl_add_u32 v11, v11, 8, v196
	v_lshl_add_u32 v12, v12, 8, v193
	v_lshl_add_u32 v13, v13, 8, v194
	v_lshl_add_u32 v14, v14, 8, v195
	v_lshl_add_u32 v15, v15, 8, v196
	ds_read_u16 v16, v187 offset:256
	ds_read_u16 v18, v187 offset:272
	ds_read_u16 v19, v187 offset:288
	ds_read_u16 v20, v187 offset:304
	ds_read_u16 v21, v187 offset:320
	ds_read_u16 v22, v187 offset:336
	ds_read_u16 v23, v187 offset:352
	ds_read_u16 v24, v187 offset:368
	s_waitcnt lgkmcnt(0)
	v_lshl_add_u32 v16, v16, 8, v193
	v_lshl_add_u32 v18, v18, 8, v194
	v_lshl_add_u32 v19, v19, 8, v195
	v_lshl_add_u32 v20, v20, 8, v196
	v_lshl_add_u32 v21, v21, 8, v193
	v_lshl_add_u32 v22, v22, 8, v194
	v_lshl_add_u32 v23, v23, 8, v195
	v_lshl_add_u32 v24, v24, 8, v196
	ds_read_u16 v25, v187 offset:384
	ds_read_u16 v26, v187 offset:400
	ds_read_u16 v27, v187 offset:416
	ds_read_u16 v28, v187 offset:432
	ds_read_u16 v29, v187 offset:448
	ds_read_u16 v30, v187 offset:464
	ds_read_u16 v31, v187 offset:480
	ds_read_u16 v219, v187 offset:496
	s_waitcnt lgkmcnt(0)
	v_lshl_add_u32 v25, v25, 8, v193
	v_lshl_add_u32 v26, v26, 8, v194
	v_lshl_add_u32 v27, v27, 8, v195
	v_lshl_add_u32 v28, v28, 8, v196
	v_lshl_add_u32 v29, v29, 8, v193
	v_lshl_add_u32 v30, v30, 8, v194
	v_lshl_add_u32 v31, v31, 8, v195
	v_lshl_add_u32 v219, v219, 8, v196
	s_waitcnt vmcnt(8)
; __device__ __forceinline__ void phase_attn(KP kp, int l, unsigned char* shm) {
;     ...
;         for (int i = 16; i < 32; ++i) {
;           const int idx = selw[i * 8 + ks8];
;           vr[i] = *(const u32x4*)(vbase + (size_t)idx * 128 + kvh * 64 + dc * 8);
;         }
; #pragma unroll
;         for (int s8 = 0; s8 < 8; ++s8) {
; #pragma unroll
;           for (int it = 0; it < 4; ++it) *(u32x4*)(tileb + (it * 8 + ks8) * 144 + dc * 16) = vr[s8 * 4 + it];
;           u32x2 t0, t1, t2, t3, t4, t5, t6, t7;
;           asm volatile(
;               "ds_read_b64_tr_b16 %0, %8\n\tds_read_b64_tr_b16 %1, %8 offset:2304\n\t"
;               "ds_read_b64_tr_b16 %2, %8 offset:32\n\tds_read_b64_tr_b16 %3, %8 offset:2336\n\t"
;               "ds_read_b64_tr_b16 %4, %8 offset:64\n\tds_read_b64_tr_b16 %5, %8 offset:2368\n\t"
;               "ds_read_b64_tr_b16 %6, %8 offset:96\n\tds_read_b64_tr_b16 %7, %8 offset:2400\n\t"
;               "s_waitcnt lgkmcnt(0)"
;               : "=&v"(t0), "=&v"(t1), "=&v"(t2), "=&v"(t3), "=&v"(t4), "=&v"(t5), "=&v"(t6), "=&v"(t7)
;               : "v"(tr_addr)
;               : "memory");
;           const bf16x8 a0 = __builtin_bit_cast(bf16x8, (u32x4){t0[0], t0[1], t1[0], t1[1]});
;           const bf16x8 a1 = __builtin_bit_cast(bf16x8, (u32x4){t2[0], t2[1], t3[0], t3[1]});
;           const bf16x8 a2 = __builtin_bit_cast(bf16x8, (u32x4){t4[0], t4[1], t5[0], t5[1]});
;           const bf16x8 a3 = __builtin_bit_cast(bf16x8, (u32x4){t6[0], t6[1], t7[0], t7[1]});
;           oacc[0] = __builtin_amdgcn_mfma_f32_16x16x32_bf16(a0, pf[s8], oacc[0], 0, 0, 0);
;           oacc[1] = __builtin_amdgcn_mfma_f32_16x16x32_bf16(a1, pf[s8], oacc[1], 0, 0, 0);
;           oacc[2] = __builtin_amdgcn_mfma_f32_16x16x32_bf16(a2, pf[s8], oacc[2], 0, 0, 0);
;           oacc[3] = __builtin_amdgcn_mfma_f32_16x16x32_bf16(a3, pf[s8], oacc[3], 0, 0, 0);
;           if (kvh == 0 && s8 == 3) {
; #pragma unroll
;             for (int k8 = 0; k8 < 8; ++k8) {
;               const int idx = selw[k8 * 16 + nn];
;               const bf16_t* kp = kbase + (size_t)idx * 128 + 64 + kg * 8;
;               kpre[k8][0] = *(const bf16x8*)kp;
;               kpre[k8][1] = *(const bf16x8*)(kp + 32);
;             }
;           }
;         }
;         __builtin_amdgcn_sched_barrier(0);
;       }
;       if (nn < 4) {
; #pragma unroll
;         for (int c = 0; c < 4; ++c) {
	ds_read_b64_tr_b16 v[160:161], v182 offset:4096
	ds_read_b64_tr_b16 v[162:163], v182 offset:6144
	ds_read_b64_tr_b16 v[164:165], v183 offset:4096
	ds_read_b64_tr_b16 v[166:167], v183 offset:6144
	ds_read_b64_tr_b16 v[168:169], v184 offset:4096
	ds_read_b64_tr_b16 v[170:171], v184 offset:6144
	ds_read_b64_tr_b16 v[172:173], v185 offset:4096
	ds_read_b64_tr_b16 v[174:175], v185 offset:6144
	s_mov_b32 m0, s46
	s_nop 0
	global_load_lds_dwordx4 v0, s[28:29]
	global_load_lds_dwordx4 v1, s[28:29] offset:1024
	global_load_lds_dwordx4 v2, s[28:29] offset:2048
	global_load_lds_dwordx4 v3, s[28:29] offset:3072
	s_waitcnt lgkmcnt(0)
	v_mfma_f32_16x16x32_bf16 v[128:131], v[160:163], v[116:119], v[128:131]
	v_mfma_f32_16x16x32_bf16 v[132:135], v[164:167], v[116:119], v[132:135]
	v_mfma_f32_16x16x32_bf16 v[136:139], v[168:171], v[116:119], v[136:139]
	v_mfma_f32_16x16x32_bf16 v[140:143], v[172:175], v[116:119], v[140:143]
	s_waitcnt vmcnt(8)
	ds_read_b64_tr_b16 v[160:161], v182 offset:8192
	ds_read_b64_tr_b16 v[162:163], v182 offset:10240
	ds_read_b64_tr_b16 v[164:165], v183 offset:8192
	ds_read_b64_tr_b16 v[166:167], v183 offset:10240
	ds_read_b64_tr_b16 v[168:169], v184 offset:8192
	ds_read_b64_tr_b16 v[170:171], v184 offset:10240
	ds_read_b64_tr_b16 v[172:173], v185 offset:8192
	ds_read_b64_tr_b16 v[174:175], v185 offset:10240
	s_mov_b32 m0, s47
	s_nop 0
	global_load_lds_dwordx4 v4, s[28:29]
	global_load_lds_dwordx4 v5, s[28:29] offset:1024
	global_load_lds_dwordx4 v6, s[28:29] offset:2048
	global_load_lds_dwordx4 v7, s[28:29] offset:3072
	s_waitcnt lgkmcnt(0)
	v_mfma_f32_16x16x32_bf16 v[128:131], v[160:163], v[120:123], v[128:131]
	v_mfma_f32_16x16x32_bf16 v[132:135], v[164:167], v[120:123], v[132:135]
	v_mfma_f32_16x16x32_bf16 v[136:139], v[168:171], v[120:123], v[136:139]
	v_mfma_f32_16x16x32_bf16 v[140:143], v[172:175], v[120:123], v[140:143]
	s_waitcnt vmcnt(8)
	ds_read_b64_tr_b16 v[160:161], v182 offset:12288
	ds_read_b64_tr_b16 v[162:163], v182 offset:14336
	ds_read_b64_tr_b16 v[164:165], v183 offset:12288
	ds_read_b64_tr_b16 v[166:167], v183 offset:14336
	ds_read_b64_tr_b16 v[168:169], v184 offset:12288
	ds_read_b64_tr_b16 v[170:171], v184 offset:14336
	ds_read_b64_tr_b16 v[172:173], v185 offset:12288
	ds_read_b64_tr_b16 v[174:175], v185 offset:14336
	s_mov_b32 m0, s48
	s_nop 0
	global_load_lds_dwordx4 v8, s[28:29]
	global_load_lds_dwordx4 v9, s[28:29] offset:1024
	global_load_lds_dwordx4 v10, s[28:29] offset:2048
	global_load_lds_dwordx4 v11, s[28:29] offset:3072
	s_waitcnt lgkmcnt(0)
	v_mfma_f32_16x16x32_bf16 v[128:131], v[160:163], v[124:127], v[128:131]
	v_mfma_f32_16x16x32_bf16 v[132:135], v[164:167], v[124:127], v[132:135]
	v_mfma_f32_16x16x32_bf16 v[136:139], v[168:171], v[124:127], v[136:139]
	v_mfma_f32_16x16x32_bf16 v[140:143], v[172:175], v[124:127], v[140:143]
	s_nop 7
	s_nop 3
	v_mul_f32_e32 v128, v208, v128
	v_mul_f32_e32 v129, v208, v129
	v_mul_f32_e32 v130, v208, v130
	v_mul_f32_e32 v131, v208, v131
	v_cvt_pk_bf16_f32 v200, v128, v129
	v_cvt_pk_bf16_f32 v201, v130, v131
	v_mul_f32_e32 v132, v208, v132
	v_mul_f32_e32 v133, v208, v133
	v_mul_f32_e32 v134, v208, v134
	v_mul_f32_e32 v135, v208, v135
	v_cvt_pk_bf16_f32 v202, v132, v133
	v_cvt_pk_bf16_f32 v203, v134, v135
	v_mul_f32_e32 v136, v208, v136
	v_mul_f32_e32 v137, v208, v137
	v_mul_f32_e32 v138, v208, v138
	v_mul_f32_e32 v139, v208, v139
	v_cvt_pk_bf16_f32 v204, v136, v137
	v_cvt_pk_bf16_f32 v205, v138, v139
	v_mul_f32_e32 v140, v208, v140
	v_mul_f32_e32 v141, v208, v141
	v_mul_f32_e32 v142, v208, v142
	v_mul_f32_e32 v143, v208, v143
	v_cvt_pk_bf16_f32 v206, v140, v141
	v_cvt_pk_bf16_f32 v207, v142, v143
	s_mov_b64 exec, s[42:43]
	global_store_dwordx2 v190, v[200:201], s[34:35] offset:512 nt
	global_store_dwordx2 v190, v[202:203], s[34:35] offset:544 nt
	global_store_dwordx2 v190, v[204:205], s[34:35] offset:576 nt
	global_store_dwordx2 v190, v[206:207], s[34:35] offset:608 nt
	s_mov_b64 exec, -1
	s_mov_b64 s[20:21], s[28:29]
	s_mov_b64 s[22:23], s[30:31]
	s_add_u32 s24, s28, 0x80
	s_addc_u32 s25, s29, 0
	s_add_u32 s26, s30, 0x80
	s_addc_u32 s27, s31, 0
	s_mov_b64 s[34:35], s[36:37]
	s_mov_b32 s44, s45
	s_mov_b32 s2, s50
	s_cmp_lt_i32 s2, 0x8200
	s_cbranch_scc1 .Lattn_loop
